# hot loop heads (GEMM K-loops, MLA and DIFF tile loops) aligned to 64 bytes
# speedup vs baseline: 1.0026x; 1.0026x over previous
; #define PG8_STAGE(bufoff, gbase, voff) do { _Pragma("unroll") for (int _i = 0; _i < 2; ++_i) \
;     __builtin_amdgcn_global_load_lds((const unsigned*)((const char*)(gbase) + (voff)[_i]), (PG8_LAS unsigned*)(lds + (bufoff) + ldsw + _i * 8192), 16, 0, 0); } while (0)
; #define PG8_WAIT_V(n) asm volatile("s_waitcnt vmcnt(" #n ")" ::: "memory")
; #define PG8_BAR __builtin_amdgcn_s_barrier()
; template <class Epi>
; DI void gemm_phase(PG8_LAS unsigned char* lds, const Gemm g, const StaticOrder& S, const Epi& E) {
;     ...
;   f32x4 acc[2][2][4][2];
; #pragma unroll
;   for (int a = 0; a < 2; ++a)
; #pragma unroll
;     for (int b = 0; b < 2; ++b)
; #pragma unroll
;       for (int m = 0; m < 4; ++m)
; #pragma unroll
;         for (int n = 0; n < 2; ++n) acc[a][b][m][n] = (f32x4){0.f, 0.f, 0.f, 0.f};
;   bf16x8 At[4][2], B0[2][2], B1[2][2];
;   const char* cA = (const char*)g.A + (size_t)cur.pm * tstepA; const char* cB = (const char*)g.Bt + (size_t)cur.pn * tstepB;
;   PG8_WAIT_V(0);
;   PG8_STAGE(PG8_SB(0, 0), cB, voffB); PG8_STAGE(PG8_SA(0, 0), cA, voffA); PG8_STAGE(PG8_SB(0, 1), cB + hstepB, voffB); PG8_STAGE(PG8_SA(0, 1), cA + hstepA, voffA);
;   if (wr == 1) PG8_BAR;
;   PG8_WAIT_V(4); PG8_BAR;
;   PG8_STAGE(PG8_SB(1, 0), cB + kstep, voffB); PG8_STAGE(PG8_SA(1, 0), cA + kstep, voffA); PG8_STAGE(PG8_SB(1, 1), cB + hstepB + kstep, voffB);
;   PG8_WAIT_V(6); PG8_BAR;
; #pragma unroll 1
;   for (;;) {
;     const bool has_next = S.next(ui + 1, nxt);
;     const char* nA = has_next ? (const char*)g.A + (size_t)nxt.pm * tstepA : cA; const char* nB = has_next ? (const char*)g.Bt + (size_t)nxt.pn * tstepB : cB;
; #pragma unroll 1
;     for (int t = 0; t < nt; t += 2) {
.LBB0_167:
	s_ashr_i32 s79, s78, 31
	s_lshl_b64 s[22:23], s[78:79], 20
	v_cmp_lt_i64_e32 vcc, s[80:81], v[142:143]
	s_add_u32 s80, s24, s22
	s_addc_u32 s81, s25, s23
	s_and_b64 s[22:23], vcc, exec
	s_cselect_b32 s11, s81, s13
	s_cselect_b32 s15, s80, s12
	s_ashr_i32 s77, s76, 31
	s_lshl_b64 s[22:23], s[76:77], 20
	s_add_u32 s82, s56, s22
	s_addc_u32 s83, s57, s23
	s_and_b64 s[22:23], vcc, exec
	s_cselect_b32 s77, s83, s85
	s_cselect_b32 s79, s82, s84
	s_add_u32 s12, s12, 0x80080
	s_addc_u32 s13, s13, 0
	s_add_u32 vcc_lo, s84, 0x100
	v_mov_b32_e32 v0, 0
	s_addc_u32 vcc_hi, s85, 0
	s_mov_b32 s3, -2
	s_waitcnt lgkmcnt(0)
	v_mov_b32_e32 v1, v0
	v_mov_b32_e32 v2, v0
	v_mov_b32_e32 v3, v0
	v_mov_b32_e32 v4, v0
	v_mov_b32_e32 v5, v0
	v_mov_b32_e32 v6, v0
	v_mov_b32_e32 v7, v0
	v_mov_b32_e32 v16, v0
	v_mov_b32_e32 v17, v0
	v_mov_b32_e32 v18, v0
	v_mov_b32_e32 v19, v0
	v_mov_b32_e32 v20, v0
	v_mov_b32_e32 v21, v0
	v_mov_b32_e32 v22, v0
	v_mov_b32_e32 v23, v0
	v_mov_b32_e32 v32, v0
	v_mov_b32_e32 v33, v0
	v_mov_b32_e32 v34, v0
	v_mov_b32_e32 v35, v0
	v_mov_b32_e32 v36, v0
	v_mov_b32_e32 v37, v0
	v_mov_b32_e32 v38, v0
	v_mov_b32_e32 v39, v0
	v_mov_b32_e32 v48, v0
	v_mov_b32_e32 v49, v0
	v_mov_b32_e32 v50, v0
	v_mov_b32_e32 v51, v0
	v_mov_b32_e32 v52, v0
	v_mov_b32_e32 v53, v0
	v_mov_b32_e32 v54, v0
	v_mov_b32_e32 v55, v0
	v_mov_b32_e32 v8, v0
	v_mov_b32_e32 v9, v0
	v_mov_b32_e32 v10, v0
	v_mov_b32_e32 v11, v0
	v_mov_b32_e32 v12, v0
	v_mov_b32_e32 v13, v0
	v_mov_b32_e32 v14, v0
	v_mov_b32_e32 v15, v0
	v_mov_b32_e32 v24, v0
	v_mov_b32_e32 v25, v0
	v_mov_b32_e32 v26, v0
	v_mov_b32_e32 v27, v0
	v_mov_b32_e32 v28, v0
	v_mov_b32_e32 v29, v0
	v_mov_b32_e32 v30, v0
	v_mov_b32_e32 v31, v0
	v_mov_b32_e32 v40, v0
	v_mov_b32_e32 v41, v0
	v_mov_b32_e32 v42, v0
	v_mov_b32_e32 v43, v0
	v_mov_b32_e32 v44, v0
	v_mov_b32_e32 v45, v0
	v_mov_b32_e32 v46, v0
	v_mov_b32_e32 v47, v0
	v_mov_b32_e32 v56, v0
	v_mov_b32_e32 v57, v0
	v_mov_b32_e32 v58, v0
	v_mov_b32_e32 v59, v0
	v_mov_b32_e32 v60, v0
	v_mov_b32_e32 v61, v0
	v_mov_b32_e32 v62, v0
	v_mov_b32_e32 v63, v0
	v_mov_b32_e32 v64, v0
	v_mov_b32_e32 v65, v0
	v_mov_b32_e32 v66, v0
	v_mov_b32_e32 v67, v0
	v_mov_b32_e32 v68, v0
	v_mov_b32_e32 v69, v0
	v_mov_b32_e32 v70, v0
	v_mov_b32_e32 v71, v0
	v_mov_b32_e32 v80, v0
	v_mov_b32_e32 v81, v0
	v_mov_b32_e32 v82, v0
	v_mov_b32_e32 v83, v0
	v_mov_b32_e32 v84, v0
	v_mov_b32_e32 v85, v0
	v_mov_b32_e32 v86, v0
	v_mov_b32_e32 v87, v0
	v_mov_b32_e32 v96, v0
	v_mov_b32_e32 v97, v0
	v_mov_b32_e32 v98, v0
	v_mov_b32_e32 v99, v0
	v_mov_b32_e32 v100, v0
	v_mov_b32_e32 v101, v0
	v_mov_b32_e32 v102, v0
	v_mov_b32_e32 v103, v0
	v_mov_b32_e32 v112, v0
	v_mov_b32_e32 v113, v0
	v_mov_b32_e32 v114, v0
	v_mov_b32_e32 v115, v0
	v_mov_b32_e32 v116, v0
	v_mov_b32_e32 v117, v0
	v_mov_b32_e32 v118, v0
	v_mov_b32_e32 v119, v0
	v_mov_b32_e32 v72, v0
	v_mov_b32_e32 v73, v0
	v_mov_b32_e32 v74, v0
	v_mov_b32_e32 v75, v0
	v_mov_b32_e32 v76, v0
	v_mov_b32_e32 v77, v0
	v_mov_b32_e32 v78, v0
	v_mov_b32_e32 v79, v0
	v_mov_b32_e32 v88, v0
	v_mov_b32_e32 v89, v0
	v_mov_b32_e32 v90, v0
	v_mov_b32_e32 v91, v0
	v_mov_b32_e32 v92, v0
	v_mov_b32_e32 v93, v0
	v_mov_b32_e32 v94, v0
	v_mov_b32_e32 v95, v0
	v_mov_b32_e32 v104, v0
	v_mov_b32_e32 v105, v0
	v_mov_b32_e32 v106, v0
	v_mov_b32_e32 v107, v0
	v_mov_b32_e32 v108, v0
	v_mov_b32_e32 v109, v0
	v_mov_b32_e32 v110, v0
	v_mov_b32_e32 v111, v0
	v_mov_b32_e32 v120, v0
	v_mov_b32_e32 v121, v0
	v_mov_b32_e32 v122, v0
	v_mov_b32_e32 v123, v0
	v_mov_b32_e32 v124, v0
	v_mov_b32_e32 v125, v0
	v_mov_b32_e32 v126, v0
	v_mov_b32_e32 v127, v0
	.p2align	6

; #define PG8_STAGE(bufoff, gbase, voff) do { _Pragma("unroll") for (int _i = 0; _i < 2; ++_i) \
;     __builtin_amdgcn_global_load_lds((const unsigned*)((const char*)(gbase) + (voff)[_i]), (PG8_LAS unsigned*)(lds + (bufoff) + ldsw + _i * 8192), 16, 0, 0); } while (0)
; #define PG8_WAIT_V(n) asm volatile("s_waitcnt vmcnt(" #n ")" ::: "memory")
; #define PG8_BAR __builtin_amdgcn_s_barrier()
; template <class Epi>
; DI void gemm_phase(PG8_LAS unsigned char* lds, const Gemm g, const StaticOrder& S, const Epi& E) {
;     ...
;   f32x4 acc[2][2][4][2];
; #pragma unroll
;   for (int a = 0; a < 2; ++a)
; #pragma unroll
;     for (int b = 0; b < 2; ++b)
; #pragma unroll
;       for (int m = 0; m < 4; ++m)
; #pragma unroll
;         for (int n = 0; n < 2; ++n) acc[a][b][m][n] = (f32x4){0.f, 0.f, 0.f, 0.f};
;   bf16x8 At[4][2], B0[2][2], B1[2][2];
;   const char* cA = (const char*)g.A + (size_t)cur.pm * tstepA; const char* cB = (const char*)g.Bt + (size_t)cur.pn * tstepB;
;   PG8_WAIT_V(0);
;   PG8_STAGE(PG8_SB(0, 0), cB, voffB); PG8_STAGE(PG8_SA(0, 0), cA, voffA); PG8_STAGE(PG8_SB(0, 1), cB + hstepB, voffB); PG8_STAGE(PG8_SA(0, 1), cA + hstepA, voffA);
;   if (wr == 1) PG8_BAR;
;   PG8_WAIT_V(4); PG8_BAR;
;   PG8_STAGE(PG8_SB(1, 0), cB + kstep, voffB); PG8_STAGE(PG8_SA(1, 0), cA + kstep, voffA); PG8_STAGE(PG8_SB(1, 1), cB + hstepB + kstep, voffB);
;   PG8_WAIT_V(6); PG8_BAR;
; #pragma unroll 1
;   for (;;) {
;     const bool has_next = S.next(ui + 1, nxt);
;     const char* nA = has_next ? (const char*)g.A + (size_t)nxt.pm * tstepA : cA; const char* nB = has_next ? (const char*)g.Bt + (size_t)nxt.pn * tstepB : cB;
; #pragma unroll 1
;     for (int t = 0; t < nt; t += 2) {
.LBB0_253:
	s_ashr_i32 s13, s12, 31
	s_lshl_b64 s[22:23], s[12:13], 18
	s_add_u32 s74, s72, s22
	s_addc_u32 s75, s73, s23
	s_and_b64 s[8:9], s[8:9], exec
	s_cselect_b32 s13, s75, s79
	s_cselect_b32 s97, s74, s78
	s_add_u32 vcc_lo, s78, 0x100
	v_mov_b32_e32 v0, 0
	s_addc_u32 vcc_hi, s79, 0
	s_mov_b32 s0, -2
	v_mov_b32_e32 v1, v0
	v_mov_b32_e32 v2, v0
	v_mov_b32_e32 v3, v0
	v_mov_b32_e32 v4, v0
	v_mov_b32_e32 v5, v0
	v_mov_b32_e32 v6, v0
	v_mov_b32_e32 v7, v0
	v_mov_b32_e32 v16, v0
	v_mov_b32_e32 v17, v0
	v_mov_b32_e32 v18, v0
	v_mov_b32_e32 v19, v0
	v_mov_b32_e32 v20, v0
	v_mov_b32_e32 v21, v0
	v_mov_b32_e32 v22, v0
	v_mov_b32_e32 v23, v0
	v_mov_b32_e32 v32, v0
	v_mov_b32_e32 v33, v0
	v_mov_b32_e32 v34, v0
	v_mov_b32_e32 v35, v0
	v_mov_b32_e32 v36, v0
	v_mov_b32_e32 v37, v0
	v_mov_b32_e32 v38, v0
	v_mov_b32_e32 v39, v0
	v_mov_b32_e32 v48, v0
	v_mov_b32_e32 v49, v0
	v_mov_b32_e32 v50, v0
	v_mov_b32_e32 v51, v0
	v_mov_b32_e32 v52, v0
	v_mov_b32_e32 v53, v0
	v_mov_b32_e32 v54, v0
	v_mov_b32_e32 v55, v0
	v_mov_b32_e32 v8, v0
	v_mov_b32_e32 v9, v0
	v_mov_b32_e32 v10, v0
	v_mov_b32_e32 v11, v0
	v_mov_b32_e32 v12, v0
	v_mov_b32_e32 v13, v0
	v_mov_b32_e32 v14, v0
	v_mov_b32_e32 v15, v0
	v_mov_b32_e32 v24, v0
	v_mov_b32_e32 v25, v0
	v_mov_b32_e32 v26, v0
	v_mov_b32_e32 v27, v0
	v_mov_b32_e32 v28, v0
	v_mov_b32_e32 v29, v0
	v_mov_b32_e32 v30, v0
	v_mov_b32_e32 v31, v0
	v_mov_b32_e32 v40, v0
	v_mov_b32_e32 v41, v0
	v_mov_b32_e32 v42, v0
	v_mov_b32_e32 v43, v0
	v_mov_b32_e32 v44, v0
	v_mov_b32_e32 v45, v0
	v_mov_b32_e32 v46, v0
	v_mov_b32_e32 v47, v0
	v_mov_b32_e32 v56, v0
	v_mov_b32_e32 v57, v0
	v_mov_b32_e32 v58, v0
	v_mov_b32_e32 v59, v0
	v_mov_b32_e32 v60, v0
	v_mov_b32_e32 v61, v0
	v_mov_b32_e32 v62, v0
	v_mov_b32_e32 v63, v0
	v_mov_b32_e32 v64, v0
	v_mov_b32_e32 v65, v0
	v_mov_b32_e32 v66, v0
	v_mov_b32_e32 v67, v0
	v_mov_b32_e32 v68, v0
	v_mov_b32_e32 v69, v0
	v_mov_b32_e32 v70, v0
	v_mov_b32_e32 v71, v0
	v_mov_b32_e32 v80, v0
	v_mov_b32_e32 v81, v0
	v_mov_b32_e32 v82, v0
	v_mov_b32_e32 v83, v0
	v_mov_b32_e32 v84, v0
	v_mov_b32_e32 v85, v0
	v_mov_b32_e32 v86, v0
	v_mov_b32_e32 v87, v0
	v_mov_b32_e32 v96, v0
	v_mov_b32_e32 v97, v0
	v_mov_b32_e32 v98, v0
	v_mov_b32_e32 v99, v0
	v_mov_b32_e32 v100, v0
	v_mov_b32_e32 v101, v0
	v_mov_b32_e32 v102, v0
	v_mov_b32_e32 v103, v0
	v_mov_b32_e32 v112, v0
	v_mov_b32_e32 v113, v0
	v_mov_b32_e32 v114, v0
	v_mov_b32_e32 v115, v0
	v_mov_b32_e32 v116, v0
	v_mov_b32_e32 v117, v0
	v_mov_b32_e32 v118, v0
	v_mov_b32_e32 v119, v0
	v_mov_b32_e32 v72, v0
	v_mov_b32_e32 v73, v0
	v_mov_b32_e32 v74, v0
	v_mov_b32_e32 v75, v0
	v_mov_b32_e32 v76, v0
	v_mov_b32_e32 v77, v0
	v_mov_b32_e32 v78, v0
	v_mov_b32_e32 v79, v0
	v_mov_b32_e32 v88, v0
	v_mov_b32_e32 v89, v0
	v_mov_b32_e32 v90, v0
	v_mov_b32_e32 v91, v0
	v_mov_b32_e32 v92, v0
	v_mov_b32_e32 v93, v0
	v_mov_b32_e32 v94, v0
	v_mov_b32_e32 v95, v0
	v_mov_b32_e32 v104, v0
	v_mov_b32_e32 v105, v0
	v_mov_b32_e32 v106, v0
	v_mov_b32_e32 v107, v0
	v_mov_b32_e32 v108, v0
	v_mov_b32_e32 v109, v0
	v_mov_b32_e32 v110, v0
	v_mov_b32_e32 v111, v0
	v_mov_b32_e32 v120, v0
	v_mov_b32_e32 v121, v0
	v_mov_b32_e32 v122, v0
	v_mov_b32_e32 v123, v0
	v_mov_b32_e32 v124, v0
	v_mov_b32_e32 v125, v0
	v_mov_b32_e32 v126, v0
	v_mov_b32_e32 v127, v0
	.p2align	6

; #define PG8_STAGE(bufoff, gbase, voff) do { _Pragma("unroll") for (int _i = 0; _i < 2; ++_i) \
;     __builtin_amdgcn_global_load_lds((const unsigned*)((const char*)(gbase) + (voff)[_i]), (PG8_LAS unsigned*)(lds + (bufoff) + ldsw + _i * 8192), 16, 0, 0); } while (0)
; #define PG8_WAIT_V(n) asm volatile("s_waitcnt vmcnt(" #n ")" ::: "memory")
; #define PG8_BAR __builtin_amdgcn_s_barrier()
; template <class Epi>
; DI void gemm_phase(PG8_LAS unsigned char* lds, const Gemm g, const StaticOrder& S, const Epi& E) {
;     ...
;   f32x4 acc[2][2][4][2];
; #pragma unroll
;   for (int a = 0; a < 2; ++a)
; #pragma unroll
;     for (int b = 0; b < 2; ++b)
; #pragma unroll
;       for (int m = 0; m < 4; ++m)
; #pragma unroll
;         for (int n = 0; n < 2; ++n) acc[a][b][m][n] = (f32x4){0.f, 0.f, 0.f, 0.f};
;   bf16x8 At[4][2], B0[2][2], B1[2][2];
;   const char* cA = (const char*)g.A + (size_t)cur.pm * tstepA; const char* cB = (const char*)g.Bt + (size_t)cur.pn * tstepB;
;   PG8_WAIT_V(0);
;   PG8_STAGE(PG8_SB(0, 0), cB, voffB); PG8_STAGE(PG8_SA(0, 0), cA, voffA); PG8_STAGE(PG8_SB(0, 1), cB + hstepB, voffB); PG8_STAGE(PG8_SA(0, 1), cA + hstepA, voffA);
;   if (wr == 1) PG8_BAR;
;   PG8_WAIT_V(4); PG8_BAR;
;   PG8_STAGE(PG8_SB(1, 0), cB + kstep, voffB); PG8_STAGE(PG8_SA(1, 0), cA + kstep, voffA); PG8_STAGE(PG8_SB(1, 1), cB + hstepB + kstep, voffB);
;   PG8_WAIT_V(6); PG8_BAR;
; #pragma unroll 1
;   for (;;) {
;     const bool has_next = S.next(ui + 1, nxt);
;     const char* nA = has_next ? (const char*)g.A + (size_t)nxt.pm * tstepA : cA; const char* nB = has_next ? (const char*)g.Bt + (size_t)nxt.pn * tstepB : cB;
; #pragma unroll 1
;     for (int t = 0; t < nt; t += 2) {
.LBB0_275:
	s_ashr_i32 s41, s40, 31
	s_lshl_b64 s[22:23], s[40:41], 18
	s_add_u32 s74, s70, s22
	s_addc_u32 s75, s71, s23
	s_and_b64 s[8:9], s[8:9], exec
	s_cselect_b32 s41, s75, s79
	s_cselect_b32 vcc_lo, s74, s78
	s_add_u32 vcc_hi, s78, 0x100
	v_mov_b32_e32 v0, 0
	s_addc_u32 s0, s79, 0
	s_mov_b32 s22, -2
	v_mov_b32_e32 v1, v0
	v_mov_b32_e32 v2, v0
	v_mov_b32_e32 v3, v0
	v_mov_b32_e32 v4, v0
	v_mov_b32_e32 v5, v0
	v_mov_b32_e32 v6, v0
	v_mov_b32_e32 v7, v0
	v_mov_b32_e32 v16, v0
	v_mov_b32_e32 v17, v0
	v_mov_b32_e32 v18, v0
	v_mov_b32_e32 v19, v0
	v_mov_b32_e32 v20, v0
	v_mov_b32_e32 v21, v0
	v_mov_b32_e32 v22, v0
	v_mov_b32_e32 v23, v0
	v_mov_b32_e32 v32, v0
	v_mov_b32_e32 v33, v0
	v_mov_b32_e32 v34, v0
	v_mov_b32_e32 v35, v0
	v_mov_b32_e32 v36, v0
	v_mov_b32_e32 v37, v0
	v_mov_b32_e32 v38, v0
	v_mov_b32_e32 v39, v0
	v_mov_b32_e32 v48, v0
	v_mov_b32_e32 v49, v0
	v_mov_b32_e32 v50, v0
	v_mov_b32_e32 v51, v0
	v_mov_b32_e32 v52, v0
	v_mov_b32_e32 v53, v0
	v_mov_b32_e32 v54, v0
	v_mov_b32_e32 v55, v0
	v_mov_b32_e32 v8, v0
	v_mov_b32_e32 v9, v0
	v_mov_b32_e32 v10, v0
	v_mov_b32_e32 v11, v0
	v_mov_b32_e32 v12, v0
	v_mov_b32_e32 v13, v0
	v_mov_b32_e32 v14, v0
	v_mov_b32_e32 v15, v0
	v_mov_b32_e32 v24, v0
	v_mov_b32_e32 v25, v0
	v_mov_b32_e32 v26, v0
	v_mov_b32_e32 v27, v0
	v_mov_b32_e32 v28, v0
	v_mov_b32_e32 v29, v0
	v_mov_b32_e32 v30, v0
	v_mov_b32_e32 v31, v0
	v_mov_b32_e32 v40, v0
	v_mov_b32_e32 v41, v0
	v_mov_b32_e32 v42, v0
	v_mov_b32_e32 v43, v0
	v_mov_b32_e32 v44, v0
	v_mov_b32_e32 v45, v0
	v_mov_b32_e32 v46, v0
	v_mov_b32_e32 v47, v0
	v_mov_b32_e32 v56, v0
	v_mov_b32_e32 v57, v0
	v_mov_b32_e32 v58, v0
	v_mov_b32_e32 v59, v0
	v_mov_b32_e32 v60, v0
	v_mov_b32_e32 v61, v0
	v_mov_b32_e32 v62, v0
	v_mov_b32_e32 v63, v0
	v_mov_b32_e32 v64, v0
	v_mov_b32_e32 v65, v0
	v_mov_b32_e32 v66, v0
	v_mov_b32_e32 v67, v0
	v_mov_b32_e32 v68, v0
	v_mov_b32_e32 v69, v0
	v_mov_b32_e32 v70, v0
	v_mov_b32_e32 v71, v0
	v_mov_b32_e32 v80, v0
	v_mov_b32_e32 v81, v0
	v_mov_b32_e32 v82, v0
	v_mov_b32_e32 v83, v0
	v_mov_b32_e32 v84, v0
	v_mov_b32_e32 v85, v0
	v_mov_b32_e32 v86, v0
	v_mov_b32_e32 v87, v0
	v_mov_b32_e32 v96, v0
	v_mov_b32_e32 v97, v0
	v_mov_b32_e32 v98, v0
	v_mov_b32_e32 v99, v0
	v_mov_b32_e32 v100, v0
	v_mov_b32_e32 v101, v0
	v_mov_b32_e32 v102, v0
	v_mov_b32_e32 v103, v0
	v_mov_b32_e32 v112, v0
	v_mov_b32_e32 v113, v0
	v_mov_b32_e32 v114, v0
	v_mov_b32_e32 v115, v0
	v_mov_b32_e32 v116, v0
	v_mov_b32_e32 v117, v0
	v_mov_b32_e32 v118, v0
	v_mov_b32_e32 v119, v0
	v_mov_b32_e32 v72, v0
	v_mov_b32_e32 v73, v0
	v_mov_b32_e32 v74, v0
	v_mov_b32_e32 v75, v0
	v_mov_b32_e32 v76, v0
	v_mov_b32_e32 v77, v0
	v_mov_b32_e32 v78, v0
	v_mov_b32_e32 v79, v0
	v_mov_b32_e32 v88, v0
	v_mov_b32_e32 v89, v0
	v_mov_b32_e32 v90, v0
	v_mov_b32_e32 v91, v0
	v_mov_b32_e32 v92, v0
	v_mov_b32_e32 v93, v0
	v_mov_b32_e32 v94, v0
	v_mov_b32_e32 v95, v0
	v_mov_b32_e32 v104, v0
	v_mov_b32_e32 v105, v0
	v_mov_b32_e32 v106, v0
	v_mov_b32_e32 v107, v0
	v_mov_b32_e32 v108, v0
	v_mov_b32_e32 v109, v0
	v_mov_b32_e32 v110, v0
	v_mov_b32_e32 v111, v0
	v_mov_b32_e32 v120, v0
	v_mov_b32_e32 v121, v0
	v_mov_b32_e32 v122, v0
	v_mov_b32_e32 v123, v0
	v_mov_b32_e32 v124, v0
	v_mov_b32_e32 v125, v0
	v_mov_b32_e32 v126, v0
	v_mov_b32_e32 v127, v0
	.p2align	6

; #define PG8_STAGE(bufoff, gbase, voff) do { _Pragma("unroll") for (int _i = 0; _i < 2; ++_i) \
;     __builtin_amdgcn_global_load_lds((const unsigned*)((const char*)(gbase) + (voff)[_i]), (PG8_LAS unsigned*)(lds + (bufoff) + ldsw + _i * 8192), 16, 0, 0); } while (0)
; #define PG8_WAIT_V(n) asm volatile("s_waitcnt vmcnt(" #n ")" ::: "memory")
; #define PG8_BAR __builtin_amdgcn_s_barrier()
; template <class Epi>
; DI void gemm_phase(PG8_LAS unsigned char* lds, const Gemm g, const StaticOrder& S, const Epi& E) {
;     ...
;   f32x4 acc[2][2][4][2];
; #pragma unroll
;   for (int a = 0; a < 2; ++a)
; #pragma unroll
;     for (int b = 0; b < 2; ++b)
; #pragma unroll
;       for (int m = 0; m < 4; ++m)
; #pragma unroll
;         for (int n = 0; n < 2; ++n) acc[a][b][m][n] = (f32x4){0.f, 0.f, 0.f, 0.f};
;   bf16x8 At[4][2], B0[2][2], B1[2][2];
;   const char* cA = (const char*)g.A + (size_t)cur.pm * tstepA; const char* cB = (const char*)g.Bt + (size_t)cur.pn * tstepB;
;   PG8_WAIT_V(0);
;   PG8_STAGE(PG8_SB(0, 0), cB, voffB); PG8_STAGE(PG8_SA(0, 0), cA, voffA); PG8_STAGE(PG8_SB(0, 1), cB + hstepB, voffB); PG8_STAGE(PG8_SA(0, 1), cA + hstepA, voffA);
;   if (wr == 1) PG8_BAR;
;   PG8_WAIT_V(4); PG8_BAR;
;   PG8_STAGE(PG8_SB(1, 0), cB + kstep, voffB); PG8_STAGE(PG8_SA(1, 0), cA + kstep, voffA); PG8_STAGE(PG8_SB(1, 1), cB + hstepB + kstep, voffB);
;   PG8_WAIT_V(6); PG8_BAR;
; #pragma unroll 1
;   for (;;) {
;     const bool has_next = S.next(ui + 1, nxt);
;     const char* nA = has_next ? (const char*)g.A + (size_t)nxt.pm * tstepA : cA; const char* nB = has_next ? (const char*)g.Bt + (size_t)nxt.pn * tstepB : cB;
; #pragma unroll 1
;     for (int t = 0; t < nt; t += 2) {
.LBB0_297:
	s_ashr_i32 s75, s74, 31
	s_lshl_b64 s[22:23], s[74:75], 18
	s_add_u32 s78, s68, s22
	s_addc_u32 s79, s69, s23
	s_and_b64 s[10:11], s[10:11], exec
	s_cselect_b32 s5, s79, s85
	s_cselect_b32 s75, s78, s84
	s_add_u32 s10, s84, 0x20080
	s_addc_u32 s11, s85, 0
	s_add_u32 s88, s82, 0x100
	v_mov_b32_e32 v0, 0
	s_addc_u32 vcc_lo, s83, 0
	s_mov_b32 vcc_hi, -2
	v_mov_b32_e32 v1, v0
	v_mov_b32_e32 v2, v0
	v_mov_b32_e32 v3, v0
	v_mov_b32_e32 v4, v0
	v_mov_b32_e32 v5, v0
	v_mov_b32_e32 v6, v0
	v_mov_b32_e32 v7, v0
	v_mov_b32_e32 v8, v0
	v_mov_b32_e32 v9, v0
	v_mov_b32_e32 v10, v0
	v_mov_b32_e32 v11, v0
	v_mov_b32_e32 v12, v0
	v_mov_b32_e32 v13, v0
	v_mov_b32_e32 v14, v0
	v_mov_b32_e32 v15, v0
	v_mov_b32_e32 v16, v0
	v_mov_b32_e32 v17, v0
	v_mov_b32_e32 v18, v0
	v_mov_b32_e32 v19, v0
	v_mov_b32_e32 v20, v0
	v_mov_b32_e32 v21, v0
	v_mov_b32_e32 v22, v0
	v_mov_b32_e32 v23, v0
	v_mov_b32_e32 v24, v0
	v_mov_b32_e32 v25, v0
	v_mov_b32_e32 v26, v0
	v_mov_b32_e32 v27, v0
	v_mov_b32_e32 v28, v0
	v_mov_b32_e32 v29, v0
	v_mov_b32_e32 v30, v0
	v_mov_b32_e32 v31, v0
	v_mov_b32_e32 v64, v0
	v_mov_b32_e32 v65, v0
	v_mov_b32_e32 v66, v0
	v_mov_b32_e32 v67, v0
	v_mov_b32_e32 v68, v0
	v_mov_b32_e32 v69, v0
	v_mov_b32_e32 v70, v0
	v_mov_b32_e32 v71, v0
	v_mov_b32_e32 v72, v0
	v_mov_b32_e32 v73, v0
	v_mov_b32_e32 v74, v0
	v_mov_b32_e32 v75, v0
	v_mov_b32_e32 v76, v0
	v_mov_b32_e32 v77, v0
	v_mov_b32_e32 v78, v0
	v_mov_b32_e32 v79, v0
	v_mov_b32_e32 v80, v0
	v_mov_b32_e32 v81, v0
	v_mov_b32_e32 v82, v0
	v_mov_b32_e32 v83, v0
	v_mov_b32_e32 v84, v0
	v_mov_b32_e32 v85, v0
	v_mov_b32_e32 v86, v0
	v_mov_b32_e32 v87, v0
	v_mov_b32_e32 v88, v0
	v_mov_b32_e32 v89, v0
	v_mov_b32_e32 v90, v0
	v_mov_b32_e32 v91, v0
	v_mov_b32_e32 v92, v0
	v_mov_b32_e32 v93, v0
	v_mov_b32_e32 v94, v0
	v_mov_b32_e32 v95, v0
	v_mov_b32_e32 v32, v0
	v_mov_b32_e32 v33, v0
	v_mov_b32_e32 v34, v0
	v_mov_b32_e32 v35, v0
	v_mov_b32_e32 v36, v0
	v_mov_b32_e32 v37, v0
	v_mov_b32_e32 v38, v0
	v_mov_b32_e32 v39, v0
	v_mov_b32_e32 v40, v0
	v_mov_b32_e32 v41, v0
	v_mov_b32_e32 v42, v0
	v_mov_b32_e32 v43, v0
	v_mov_b32_e32 v44, v0
	v_mov_b32_e32 v45, v0
	v_mov_b32_e32 v46, v0
	v_mov_b32_e32 v47, v0
	v_mov_b32_e32 v48, v0
	v_mov_b32_e32 v49, v0
	v_mov_b32_e32 v50, v0
	v_mov_b32_e32 v51, v0
	v_mov_b32_e32 v52, v0
	v_mov_b32_e32 v53, v0
	v_mov_b32_e32 v54, v0
	v_mov_b32_e32 v55, v0
	v_mov_b32_e32 v56, v0
	v_mov_b32_e32 v57, v0
	v_mov_b32_e32 v58, v0
	v_mov_b32_e32 v59, v0
	v_mov_b32_e32 v60, v0
	v_mov_b32_e32 v61, v0
	v_mov_b32_e32 v62, v0
	v_mov_b32_e32 v63, v0
	v_mov_b32_e32 v96, v0
	v_mov_b32_e32 v97, v0
	v_mov_b32_e32 v98, v0
	v_mov_b32_e32 v99, v0
	v_mov_b32_e32 v100, v0
	v_mov_b32_e32 v101, v0
	v_mov_b32_e32 v102, v0
	v_mov_b32_e32 v103, v0
	v_mov_b32_e32 v104, v0
	v_mov_b32_e32 v105, v0
	v_mov_b32_e32 v106, v0
	v_mov_b32_e32 v107, v0
	v_mov_b32_e32 v108, v0
	v_mov_b32_e32 v109, v0
	v_mov_b32_e32 v110, v0
	v_mov_b32_e32 v111, v0
	v_mov_b32_e32 v112, v0
	v_mov_b32_e32 v113, v0
	v_mov_b32_e32 v114, v0
	v_mov_b32_e32 v115, v0
	v_mov_b32_e32 v116, v0
	v_mov_b32_e32 v117, v0
	v_mov_b32_e32 v118, v0
	v_mov_b32_e32 v119, v0
	v_mov_b32_e32 v120, v0
	v_mov_b32_e32 v121, v0
	v_mov_b32_e32 v122, v0
	v_mov_b32_e32 v123, v0
	v_mov_b32_e32 v124, v0
	v_mov_b32_e32 v125, v0
	v_mov_b32_e32 v126, v0
	v_mov_b32_e32 v127, v0
	.p2align	6

; template <bool DIFF>
; DI void attn_phase(const AttnArgs& a, char* lds) {
;     ...
; #pragma unroll 1
;     for (int t = t_beg; t < t_end; ++t) {
.Lmla_noprio:
	.p2align	6

; #define PG8_STAGE(bufoff, gbase, voff) do { _Pragma("unroll") for (int _i = 0; _i < 2; ++_i) \
;     __builtin_amdgcn_global_load_lds((const unsigned*)((const char*)(gbase) + (voff)[_i]), (PG8_LAS unsigned*)(lds + (bufoff) + ldsw + _i * 8192), 16, 0, 0); } while (0)
; #define PG8_WAIT_V(n) asm volatile("s_waitcnt vmcnt(" #n ")" ::: "memory")
; #define PG8_BAR __builtin_amdgcn_s_barrier()
; template <class Epi>
; DI void gemm_phase(PG8_LAS unsigned char* lds, const Gemm g, const StaticOrder& S, const Epi& E) {
;     ...
;   f32x4 acc[2][2][4][2];
; #pragma unroll
;   for (int a = 0; a < 2; ++a)
; #pragma unroll
;     for (int b = 0; b < 2; ++b)
; #pragma unroll
;       for (int m = 0; m < 4; ++m)
; #pragma unroll
;         for (int n = 0; n < 2; ++n) acc[a][b][m][n] = (f32x4){0.f, 0.f, 0.f, 0.f};
;   bf16x8 At[4][2], B0[2][2], B1[2][2];
;   const char* cA = (const char*)g.A + (size_t)cur.pm * tstepA; const char* cB = (const char*)g.Bt + (size_t)cur.pn * tstepB;
;   PG8_WAIT_V(0);
;   PG8_STAGE(PG8_SB(0, 0), cB, voffB); PG8_STAGE(PG8_SA(0, 0), cA, voffA); PG8_STAGE(PG8_SB(0, 1), cB + hstepB, voffB); PG8_STAGE(PG8_SA(0, 1), cA + hstepA, voffA);
;   if (wr == 1) PG8_BAR;
;   PG8_WAIT_V(4); PG8_BAR;
;   PG8_STAGE(PG8_SB(1, 0), cB + kstep, voffB); PG8_STAGE(PG8_SA(1, 0), cA + kstep, voffA); PG8_STAGE(PG8_SB(1, 1), cB + hstepB + kstep, voffB);
;   PG8_WAIT_V(6); PG8_BAR;
; #pragma unroll 1
;   for (;;) {
;     const bool has_next = S.next(ui + 1, nxt);
;     const char* nA = has_next ? (const char*)g.A + (size_t)nxt.pm * tstepA : cA; const char* nB = has_next ? (const char*)g.Bt + (size_t)nxt.pn * tstepB : cB;
; #pragma unroll 1
;     for (int t = 0; t < nt; t += 2) {
.LBB0_434:
	s_ashr_i32 s17, s16, 31
	s_lshl_b64 s[0:1], s[16:17], 20
	v_cmp_lt_i64_e32 vcc, s[18:19], v[142:143]
	s_add_u32 s18, s24, s0
	s_addc_u32 s19, s25, s1
	s_and_b64 s[0:1], vcc, exec
	s_cselect_b32 s0, s19, s77
	s_cselect_b32 s1, s18, s76
	s_ashr_i32 s15, s14, 31
	s_lshl_b64 s[4:5], s[14:15], 20
	s_add_u32 s70, s66, s4
	s_addc_u32 s71, s67, s5
	s_and_b64 s[4:5], vcc, exec
	s_cselect_b32 s4, s71, s79
	s_cselect_b32 s5, s70, s78
	s_add_u32 s76, s76, 0x80080
	s_addc_u32 s77, s77, 0
	s_add_u32 s6, s78, 0x100
	v_mov_b32_e32 v0, 0
	s_addc_u32 s7, s79, 0
	s_mov_b32 s15, -2
	s_waitcnt lgkmcnt(0)
	v_mov_b32_e32 v1, v0
	v_mov_b32_e32 v2, v0
	v_mov_b32_e32 v3, v0
	v_mov_b32_e32 v4, v0
	v_mov_b32_e32 v5, v0
	v_mov_b32_e32 v6, v0
	v_mov_b32_e32 v7, v0
	v_mov_b32_e32 v16, v0
	v_mov_b32_e32 v17, v0
	v_mov_b32_e32 v18, v0
	v_mov_b32_e32 v19, v0
	v_mov_b32_e32 v20, v0
	v_mov_b32_e32 v21, v0
	v_mov_b32_e32 v22, v0
	v_mov_b32_e32 v23, v0
	v_mov_b32_e32 v32, v0
	v_mov_b32_e32 v33, v0
	v_mov_b32_e32 v34, v0
	v_mov_b32_e32 v35, v0
	v_mov_b32_e32 v36, v0
	v_mov_b32_e32 v37, v0
	v_mov_b32_e32 v38, v0
	v_mov_b32_e32 v39, v0
	v_mov_b32_e32 v48, v0
	v_mov_b32_e32 v49, v0
	v_mov_b32_e32 v50, v0
	v_mov_b32_e32 v51, v0
	v_mov_b32_e32 v52, v0
	v_mov_b32_e32 v53, v0
	v_mov_b32_e32 v54, v0
	v_mov_b32_e32 v55, v0
	v_mov_b32_e32 v8, v0
	v_mov_b32_e32 v9, v0
	v_mov_b32_e32 v10, v0
	v_mov_b32_e32 v11, v0
	v_mov_b32_e32 v12, v0
	v_mov_b32_e32 v13, v0
	v_mov_b32_e32 v14, v0
	v_mov_b32_e32 v15, v0
	v_mov_b32_e32 v24, v0
	v_mov_b32_e32 v25, v0
	v_mov_b32_e32 v26, v0
	v_mov_b32_e32 v27, v0
	v_mov_b32_e32 v28, v0
	v_mov_b32_e32 v29, v0
	v_mov_b32_e32 v30, v0
	v_mov_b32_e32 v31, v0
	v_mov_b32_e32 v40, v0
	v_mov_b32_e32 v41, v0
	v_mov_b32_e32 v42, v0
	v_mov_b32_e32 v43, v0
	v_mov_b32_e32 v44, v0
	v_mov_b32_e32 v45, v0
	v_mov_b32_e32 v46, v0
	v_mov_b32_e32 v47, v0
	v_mov_b32_e32 v56, v0
	v_mov_b32_e32 v57, v0
	v_mov_b32_e32 v58, v0
	v_mov_b32_e32 v59, v0
	v_mov_b32_e32 v60, v0
	v_mov_b32_e32 v61, v0
	v_mov_b32_e32 v62, v0
	v_mov_b32_e32 v63, v0
	v_mov_b32_e32 v64, v0
	v_mov_b32_e32 v65, v0
	v_mov_b32_e32 v66, v0
	v_mov_b32_e32 v67, v0
	v_mov_b32_e32 v68, v0
	v_mov_b32_e32 v69, v0
	v_mov_b32_e32 v70, v0
	v_mov_b32_e32 v71, v0
	v_mov_b32_e32 v80, v0
	v_mov_b32_e32 v81, v0
	v_mov_b32_e32 v82, v0
	v_mov_b32_e32 v83, v0
	v_mov_b32_e32 v84, v0
	v_mov_b32_e32 v85, v0
	v_mov_b32_e32 v86, v0
	v_mov_b32_e32 v87, v0
	v_mov_b32_e32 v96, v0
	v_mov_b32_e32 v97, v0
	v_mov_b32_e32 v98, v0
	v_mov_b32_e32 v99, v0
	v_mov_b32_e32 v100, v0
	v_mov_b32_e32 v101, v0
	v_mov_b32_e32 v102, v0
	v_mov_b32_e32 v103, v0
	v_mov_b32_e32 v112, v0
	v_mov_b32_e32 v113, v0
	v_mov_b32_e32 v114, v0
	v_mov_b32_e32 v115, v0
	v_mov_b32_e32 v116, v0
	v_mov_b32_e32 v117, v0
	v_mov_b32_e32 v118, v0
	v_mov_b32_e32 v119, v0
	v_mov_b32_e32 v72, v0
	v_mov_b32_e32 v73, v0
	v_mov_b32_e32 v74, v0
	v_mov_b32_e32 v75, v0
	v_mov_b32_e32 v76, v0
	v_mov_b32_e32 v77, v0
	v_mov_b32_e32 v78, v0
	v_mov_b32_e32 v79, v0
	v_mov_b32_e32 v88, v0
	v_mov_b32_e32 v89, v0
	v_mov_b32_e32 v90, v0
	v_mov_b32_e32 v91, v0
	v_mov_b32_e32 v92, v0
	v_mov_b32_e32 v93, v0
	v_mov_b32_e32 v94, v0
	v_mov_b32_e32 v95, v0
	v_mov_b32_e32 v104, v0
	v_mov_b32_e32 v105, v0
	v_mov_b32_e32 v106, v0
	v_mov_b32_e32 v107, v0
	v_mov_b32_e32 v108, v0
	v_mov_b32_e32 v109, v0
	v_mov_b32_e32 v110, v0
	v_mov_b32_e32 v111, v0
	v_mov_b32_e32 v120, v0
	v_mov_b32_e32 v121, v0
	v_mov_b32_e32 v122, v0
	v_mov_b32_e32 v123, v0
	v_mov_b32_e32 v124, v0
	v_mov_b32_e32 v125, v0
	v_mov_b32_e32 v126, v0
	v_mov_b32_e32 v127, v0
	.p2align	6

; #define PG8_STAGE(bufoff, gbase, voff) do { _Pragma("unroll") for (int _i = 0; _i < 2; ++_i) \
;     __builtin_amdgcn_global_load_lds((const unsigned*)((const char*)(gbase) + (voff)[_i]), (PG8_LAS unsigned*)(lds + (bufoff) + ldsw + _i * 8192), 16, 0, 0); } while (0)
; #define PG8_WAIT_V(n) asm volatile("s_waitcnt vmcnt(" #n ")" ::: "memory")
; #define PG8_BAR __builtin_amdgcn_s_barrier()
; template <class Epi>
; DI void gemm_phase(PG8_LAS unsigned char* lds, const Gemm g, const StaticOrder& S, const Epi& E) {
;     ...
;   f32x4 acc[2][2][4][2];
; #pragma unroll
;   for (int a = 0; a < 2; ++a)
; #pragma unroll
;     for (int b = 0; b < 2; ++b)
; #pragma unroll
;       for (int m = 0; m < 4; ++m)
; #pragma unroll
;         for (int n = 0; n < 2; ++n) acc[a][b][m][n] = (f32x4){0.f, 0.f, 0.f, 0.f};
;   bf16x8 At[4][2], B0[2][2], B1[2][2];
;   const char* cA = (const char*)g.A + (size_t)cur.pm * tstepA; const char* cB = (const char*)g.Bt + (size_t)cur.pn * tstepB;
;   PG8_WAIT_V(0);
;   PG8_STAGE(PG8_SB(0, 0), cB, voffB); PG8_STAGE(PG8_SA(0, 0), cA, voffA); PG8_STAGE(PG8_SB(0, 1), cB + hstepB, voffB); PG8_STAGE(PG8_SA(0, 1), cA + hstepA, voffA);
;   if (wr == 1) PG8_BAR;
;   PG8_WAIT_V(4); PG8_BAR;
;   PG8_STAGE(PG8_SB(1, 0), cB + kstep, voffB); PG8_STAGE(PG8_SA(1, 0), cA + kstep, voffA); PG8_STAGE(PG8_SB(1, 1), cB + hstepB + kstep, voffB);
;   PG8_WAIT_V(6); PG8_BAR;
; #pragma unroll 1
;   for (;;) {
;     const bool has_next = S.next(ui + 1, nxt);
;     const char* nA = has_next ? (const char*)g.A + (size_t)nxt.pm * tstepA : cA; const char* nB = has_next ? (const char*)g.Bt + (size_t)nxt.pn * tstepB : cB;
; #pragma unroll 1
;     for (int t = 0; t < nt; t += 2) {
.LBB0_479:
	s_ashr_i32 s13, s12, 31
	v_cmp_lt_i64_e32 vcc, s[14:15], v[142:143]
	s_lshl_b64 s[14:15], s[12:13], 20
	s_add_u32 s14, s42, s14
	s_addc_u32 s15, s43, s15
	s_and_b64 s[16:17], vcc, exec
	s_cselect_b32 s13, s15, s37
	s_cselect_b32 s82, s14, s36
	s_ashr_i32 s11, s10, 31
	s_lshl_b64 s[16:17], s[10:11], 20
	s_add_u32 s16, s64, s16
	s_addc_u32 s17, s65, s17
	s_and_b64 s[22:23], vcc, exec
	s_cselect_b32 s11, s17, s67
	s_cselect_b32 s83, s16, s66
	s_add_u32 s36, s36, 0x80080
	s_addc_u32 s37, s37, 0
	s_add_u32 s84, s66, 0x100
	v_mov_b32_e32 v0, 0
	s_addc_u32 s85, s67, 0
	s_mov_b32 s86, -2
	v_mov_b32_e32 v1, v0
	v_mov_b32_e32 v2, v0
	v_mov_b32_e32 v3, v0
	v_mov_b32_e32 v4, v0
	v_mov_b32_e32 v5, v0
	v_mov_b32_e32 v6, v0
	v_mov_b32_e32 v7, v0
	v_mov_b32_e32 v16, v0
	v_mov_b32_e32 v17, v0
	v_mov_b32_e32 v18, v0
	v_mov_b32_e32 v19, v0
	v_mov_b32_e32 v20, v0
	v_mov_b32_e32 v21, v0
	v_mov_b32_e32 v22, v0
	v_mov_b32_e32 v23, v0
	v_mov_b32_e32 v32, v0
	v_mov_b32_e32 v33, v0
	v_mov_b32_e32 v34, v0
	v_mov_b32_e32 v35, v0
	v_mov_b32_e32 v36, v0
	v_mov_b32_e32 v37, v0
	v_mov_b32_e32 v38, v0
	v_mov_b32_e32 v39, v0
	v_mov_b32_e32 v48, v0
	v_mov_b32_e32 v49, v0
	v_mov_b32_e32 v50, v0
	v_mov_b32_e32 v51, v0
	v_mov_b32_e32 v52, v0
	v_mov_b32_e32 v53, v0
	v_mov_b32_e32 v54, v0
	v_mov_b32_e32 v55, v0
	v_mov_b32_e32 v8, v0
	v_mov_b32_e32 v9, v0
	v_mov_b32_e32 v10, v0
	v_mov_b32_e32 v11, v0
	v_mov_b32_e32 v12, v0
	v_mov_b32_e32 v13, v0
	v_mov_b32_e32 v14, v0
	v_mov_b32_e32 v15, v0
	v_mov_b32_e32 v24, v0
	v_mov_b32_e32 v25, v0
	v_mov_b32_e32 v26, v0
	v_mov_b32_e32 v27, v0
	v_mov_b32_e32 v28, v0
	v_mov_b32_e32 v29, v0
	v_mov_b32_e32 v30, v0
	v_mov_b32_e32 v31, v0
	v_mov_b32_e32 v40, v0
	v_mov_b32_e32 v41, v0
	v_mov_b32_e32 v42, v0
	v_mov_b32_e32 v43, v0
	v_mov_b32_e32 v44, v0
	v_mov_b32_e32 v45, v0
	v_mov_b32_e32 v46, v0
	v_mov_b32_e32 v47, v0
	v_mov_b32_e32 v56, v0
	v_mov_b32_e32 v57, v0
	v_mov_b32_e32 v58, v0
	v_mov_b32_e32 v59, v0
	v_mov_b32_e32 v60, v0
	v_mov_b32_e32 v61, v0
	v_mov_b32_e32 v62, v0
	v_mov_b32_e32 v63, v0
	v_mov_b32_e32 v64, v0
	v_mov_b32_e32 v65, v0
	v_mov_b32_e32 v66, v0
	v_mov_b32_e32 v67, v0
	v_mov_b32_e32 v68, v0
	v_mov_b32_e32 v69, v0
	v_mov_b32_e32 v70, v0
	v_mov_b32_e32 v71, v0
	v_mov_b32_e32 v80, v0
	v_mov_b32_e32 v81, v0
	v_mov_b32_e32 v82, v0
	v_mov_b32_e32 v83, v0
	v_mov_b32_e32 v84, v0
	v_mov_b32_e32 v85, v0
	v_mov_b32_e32 v86, v0
	v_mov_b32_e32 v87, v0
	v_mov_b32_e32 v96, v0
	v_mov_b32_e32 v97, v0
	v_mov_b32_e32 v98, v0
	v_mov_b32_e32 v99, v0
	v_mov_b32_e32 v100, v0
	v_mov_b32_e32 v101, v0
	v_mov_b32_e32 v102, v0
	v_mov_b32_e32 v103, v0
	v_mov_b32_e32 v112, v0
	v_mov_b32_e32 v113, v0
	v_mov_b32_e32 v114, v0
	v_mov_b32_e32 v115, v0
	v_mov_b32_e32 v116, v0
	v_mov_b32_e32 v117, v0
	v_mov_b32_e32 v118, v0
	v_mov_b32_e32 v119, v0
	v_mov_b32_e32 v72, v0
	v_mov_b32_e32 v73, v0
	v_mov_b32_e32 v74, v0
	v_mov_b32_e32 v75, v0
	v_mov_b32_e32 v76, v0
	v_mov_b32_e32 v77, v0
	v_mov_b32_e32 v78, v0
	v_mov_b32_e32 v79, v0
	v_mov_b32_e32 v88, v0
	v_mov_b32_e32 v89, v0
	v_mov_b32_e32 v90, v0
	v_mov_b32_e32 v91, v0
	v_mov_b32_e32 v92, v0
	v_mov_b32_e32 v93, v0
	v_mov_b32_e32 v94, v0
	v_mov_b32_e32 v95, v0
	v_mov_b32_e32 v104, v0
	v_mov_b32_e32 v105, v0
	v_mov_b32_e32 v106, v0
	v_mov_b32_e32 v107, v0
	v_mov_b32_e32 v108, v0
	v_mov_b32_e32 v109, v0
	v_mov_b32_e32 v110, v0
	v_mov_b32_e32 v111, v0
	v_mov_b32_e32 v120, v0
	v_mov_b32_e32 v121, v0
	v_mov_b32_e32 v122, v0
	v_mov_b32_e32 v123, v0
	v_mov_b32_e32 v124, v0
	v_mov_b32_e32 v125, v0
	v_mov_b32_e32 v126, v0
	v_mov_b32_e32 v127, v0
	.p2align	6

; #define PG8_STAGE(bufoff, gbase, voff) do { _Pragma("unroll") for (int _i = 0; _i < 2; ++_i) \
;     __builtin_amdgcn_global_load_lds((const unsigned*)((const char*)(gbase) + (voff)[_i]), (PG8_LAS unsigned*)(lds + (bufoff) + ldsw + _i * 8192), 16, 0, 0); } while (0)
; #define PG8_WAIT_V(n) asm volatile("s_waitcnt vmcnt(" #n ")" ::: "memory")
; #define PG8_BAR __builtin_amdgcn_s_barrier()
; template <class Epi>
; DI void gemm_phase(PG8_LAS unsigned char* lds, const Gemm g, const StaticOrder& S, const Epi& E) {
;     ...
;   f32x4 acc[2][2][4][2];
; #pragma unroll
;   for (int a = 0; a < 2; ++a)
; #pragma unroll
;     for (int b = 0; b < 2; ++b)
; #pragma unroll
;       for (int m = 0; m < 4; ++m)
; #pragma unroll
;         for (int n = 0; n < 2; ++n) acc[a][b][m][n] = (f32x4){0.f, 0.f, 0.f, 0.f};
;   bf16x8 At[4][2], B0[2][2], B1[2][2];
;   const char* cA = (const char*)g.A + (size_t)cur.pm * tstepA; const char* cB = (const char*)g.Bt + (size_t)cur.pn * tstepB;
;   PG8_WAIT_V(0);
;   PG8_STAGE(PG8_SB(0, 0), cB, voffB); PG8_STAGE(PG8_SA(0, 0), cA, voffA); PG8_STAGE(PG8_SB(0, 1), cB + hstepB, voffB); PG8_STAGE(PG8_SA(0, 1), cA + hstepA, voffA);
;   if (wr == 1) PG8_BAR;
;   PG8_WAIT_V(4); PG8_BAR;
;   PG8_STAGE(PG8_SB(1, 0), cB + kstep, voffB); PG8_STAGE(PG8_SA(1, 0), cA + kstep, voffA); PG8_STAGE(PG8_SB(1, 1), cB + hstepB + kstep, voffB);
;   PG8_WAIT_V(6); PG8_BAR;
; #pragma unroll 1
;   for (;;) {
;     const bool has_next = S.next(ui + 1, nxt);
;     const char* nA = has_next ? (const char*)g.A + (size_t)nxt.pm * tstepA : cA; const char* nB = has_next ? (const char*)g.Bt + (size_t)nxt.pn * tstepB : cB;
; #pragma unroll 1
;     for (int t = 0; t < nt; t += 2) {
.LBB0_499:
	s_ashr_i32 s13, s12, 31
	v_cmp_lt_i64_e32 vcc, s[14:15], v[142:143]
	s_lshl_b64 s[14:15], s[12:13], 20
	s_add_u32 s14, s42, s14
	s_addc_u32 s15, s43, s15
	s_and_b64 s[16:17], vcc, exec
	s_cselect_b32 s13, s15, s37
	s_cselect_b32 s80, s14, s36
	s_ashr_i32 s11, s10, 31
	s_lshl_b64 s[16:17], s[10:11], 20
	s_add_u32 s16, s20, s16
	s_addc_u32 s17, s21, s17
	s_and_b64 s[22:23], vcc, exec
	s_cselect_b32 s11, s17, s65
	s_cselect_b32 s81, s16, s64
	s_add_u32 s36, s36, 0x80080
	s_addc_u32 s37, s37, 0
	s_add_u32 s82, s64, 0x100
	v_mov_b32_e32 v0, 0
	s_addc_u32 s83, s65, 0
	s_mov_b32 s84, -2
	v_mov_b32_e32 v1, v0
	v_mov_b32_e32 v2, v0
	v_mov_b32_e32 v3, v0
	v_mov_b32_e32 v4, v0
	v_mov_b32_e32 v5, v0
	v_mov_b32_e32 v6, v0
	v_mov_b32_e32 v7, v0
	v_mov_b32_e32 v16, v0
	v_mov_b32_e32 v17, v0
	v_mov_b32_e32 v18, v0
	v_mov_b32_e32 v19, v0
	v_mov_b32_e32 v20, v0
	v_mov_b32_e32 v21, v0
	v_mov_b32_e32 v22, v0
	v_mov_b32_e32 v23, v0
	v_mov_b32_e32 v32, v0
	v_mov_b32_e32 v33, v0
	v_mov_b32_e32 v34, v0
	v_mov_b32_e32 v35, v0
	v_mov_b32_e32 v36, v0
	v_mov_b32_e32 v37, v0
	v_mov_b32_e32 v38, v0
	v_mov_b32_e32 v39, v0
	v_mov_b32_e32 v48, v0
	v_mov_b32_e32 v49, v0
	v_mov_b32_e32 v50, v0
	v_mov_b32_e32 v51, v0
	v_mov_b32_e32 v52, v0
	v_mov_b32_e32 v53, v0
	v_mov_b32_e32 v54, v0
	v_mov_b32_e32 v55, v0
	v_mov_b32_e32 v8, v0
	v_mov_b32_e32 v9, v0
	v_mov_b32_e32 v10, v0
	v_mov_b32_e32 v11, v0
	v_mov_b32_e32 v12, v0
	v_mov_b32_e32 v13, v0
	v_mov_b32_e32 v14, v0
	v_mov_b32_e32 v15, v0
	v_mov_b32_e32 v24, v0
	v_mov_b32_e32 v25, v0
	v_mov_b32_e32 v26, v0
	v_mov_b32_e32 v27, v0
	v_mov_b32_e32 v28, v0
	v_mov_b32_e32 v29, v0
	v_mov_b32_e32 v30, v0
	v_mov_b32_e32 v31, v0
	v_mov_b32_e32 v40, v0
	v_mov_b32_e32 v41, v0
	v_mov_b32_e32 v42, v0
	v_mov_b32_e32 v43, v0
	v_mov_b32_e32 v44, v0
	v_mov_b32_e32 v45, v0
	v_mov_b32_e32 v46, v0
	v_mov_b32_e32 v47, v0
	v_mov_b32_e32 v56, v0
	v_mov_b32_e32 v57, v0
	v_mov_b32_e32 v58, v0
	v_mov_b32_e32 v59, v0
	v_mov_b32_e32 v60, v0
	v_mov_b32_e32 v61, v0
	v_mov_b32_e32 v62, v0
	v_mov_b32_e32 v63, v0
	v_mov_b32_e32 v64, v0
	v_mov_b32_e32 v65, v0
	v_mov_b32_e32 v66, v0
	v_mov_b32_e32 v67, v0
	v_mov_b32_e32 v68, v0
	v_mov_b32_e32 v69, v0
	v_mov_b32_e32 v70, v0
	v_mov_b32_e32 v71, v0
	v_mov_b32_e32 v80, v0
	v_mov_b32_e32 v81, v0
	v_mov_b32_e32 v82, v0
	v_mov_b32_e32 v83, v0
	v_mov_b32_e32 v84, v0
	v_mov_b32_e32 v85, v0
	v_mov_b32_e32 v86, v0
	v_mov_b32_e32 v87, v0
	v_mov_b32_e32 v96, v0
	v_mov_b32_e32 v97, v0
	v_mov_b32_e32 v98, v0
	v_mov_b32_e32 v99, v0
	v_mov_b32_e32 v100, v0
	v_mov_b32_e32 v101, v0
	v_mov_b32_e32 v102, v0
	v_mov_b32_e32 v103, v0
	v_mov_b32_e32 v112, v0
	v_mov_b32_e32 v113, v0
	v_mov_b32_e32 v114, v0
	v_mov_b32_e32 v115, v0
	v_mov_b32_e32 v116, v0
	v_mov_b32_e32 v117, v0
	v_mov_b32_e32 v118, v0
	v_mov_b32_e32 v119, v0
	v_mov_b32_e32 v72, v0
	v_mov_b32_e32 v73, v0
	v_mov_b32_e32 v74, v0
	v_mov_b32_e32 v75, v0
	v_mov_b32_e32 v76, v0
	v_mov_b32_e32 v77, v0
	v_mov_b32_e32 v78, v0
	v_mov_b32_e32 v79, v0
	v_mov_b32_e32 v88, v0
	v_mov_b32_e32 v89, v0
	v_mov_b32_e32 v90, v0
	v_mov_b32_e32 v91, v0
	v_mov_b32_e32 v92, v0
	v_mov_b32_e32 v93, v0
	v_mov_b32_e32 v94, v0
	v_mov_b32_e32 v95, v0
	v_mov_b32_e32 v104, v0
	v_mov_b32_e32 v105, v0
	v_mov_b32_e32 v106, v0
	v_mov_b32_e32 v107, v0
	v_mov_b32_e32 v108, v0
	v_mov_b32_e32 v109, v0
	v_mov_b32_e32 v110, v0
	v_mov_b32_e32 v111, v0
	v_mov_b32_e32 v120, v0
	v_mov_b32_e32 v121, v0
	v_mov_b32_e32 v122, v0
	v_mov_b32_e32 v123, v0
	v_mov_b32_e32 v124, v0
	v_mov_b32_e32 v125, v0
	v_mov_b32_e32 v126, v0
	v_mov_b32_e32 v127, v0
	.p2align	6

; #define PG8_STAGE(bufoff, gbase, voff) do { _Pragma("unroll") for (int _i = 0; _i < 2; ++_i) \
;     __builtin_amdgcn_global_load_lds((const unsigned*)((const char*)(gbase) + (voff)[_i]), (PG8_LAS unsigned*)(lds + (bufoff) + ldsw + _i * 8192), 16, 0, 0); } while (0)
; #define PG8_WAIT_V(n) asm volatile("s_waitcnt vmcnt(" #n ")" ::: "memory")
; #define PG8_BAR __builtin_amdgcn_s_barrier()
; template <class Epi>
; DI void gemm_phase(PG8_LAS unsigned char* lds, const Gemm g, const StaticOrder& S, const Epi& E) {
;     ...
;   f32x4 acc[2][2][4][2];
; #pragma unroll
;   for (int a = 0; a < 2; ++a)
; #pragma unroll
;     for (int b = 0; b < 2; ++b)
; #pragma unroll
;       for (int m = 0; m < 4; ++m)
; #pragma unroll
;         for (int n = 0; n < 2; ++n) acc[a][b][m][n] = (f32x4){0.f, 0.f, 0.f, 0.f};
;   bf16x8 At[4][2], B0[2][2], B1[2][2];
;   const char* cA = (const char*)g.A + (size_t)cur.pm * tstepA; const char* cB = (const char*)g.Bt + (size_t)cur.pn * tstepB;
;   PG8_WAIT_V(0);
;   PG8_STAGE(PG8_SB(0, 0), cB, voffB); PG8_STAGE(PG8_SA(0, 0), cA, voffA); PG8_STAGE(PG8_SB(0, 1), cB + hstepB, voffB); PG8_STAGE(PG8_SA(0, 1), cA + hstepA, voffA);
;   if (wr == 1) PG8_BAR;
;   PG8_WAIT_V(4); PG8_BAR;
;   PG8_STAGE(PG8_SB(1, 0), cB + kstep, voffB); PG8_STAGE(PG8_SA(1, 0), cA + kstep, voffA); PG8_STAGE(PG8_SB(1, 1), cB + hstepB + kstep, voffB);
;   PG8_WAIT_V(6); PG8_BAR;
; #pragma unroll 1
;   for (;;) {
;     const bool has_next = S.next(ui + 1, nxt);
;     const char* nA = has_next ? (const char*)g.A + (size_t)nxt.pm * tstepA : cA; const char* nB = has_next ? (const char*)g.Bt + (size_t)nxt.pn * tstepB : cB;
; #pragma unroll 1
;     for (int t = 0; t < nt; t += 2) {
.LBB0_519:
	s_ashr_i32 s77, s76, 31
	v_cmp_lt_i64_e32 vcc, s[14:15], v[142:143]
	s_lshl_b64 s[14:15], s[76:77], 20
	s_add_u32 s78, s60, s14
	s_addc_u32 s79, s61, s15
	s_and_b64 s[14:15], vcc, exec
	s_cselect_b32 s16, s79, s11
	s_cselect_b32 s17, s78, s10
	s_ashr_i32 s75, s74, 31
	s_lshl_b64 s[14:15], s[74:75], 20
	s_add_u32 s80, s42, s14
	s_addc_u32 s81, s43, s15
	s_and_b64 s[14:15], vcc, exec
	s_cselect_b32 s18, s81, s13
	s_cselect_b32 s19, s80, s12
	s_add_u32 s10, s10, 0x80080
	s_addc_u32 s11, s11, 0
	s_add_u32 s20, s12, 0x100
	v_mov_b32_e32 v0, 0
	s_addc_u32 s21, s13, 0
	s_mov_b32 s75, -2
	v_mov_b32_e32 v1, v0
	v_mov_b32_e32 v2, v0
	v_mov_b32_e32 v3, v0
	v_mov_b32_e32 v4, v0
	v_mov_b32_e32 v5, v0
	v_mov_b32_e32 v6, v0
	v_mov_b32_e32 v7, v0
	v_mov_b32_e32 v8, v0
	v_mov_b32_e32 v9, v0
	v_mov_b32_e32 v10, v0
	v_mov_b32_e32 v11, v0
	v_mov_b32_e32 v12, v0
	v_mov_b32_e32 v13, v0
	v_mov_b32_e32 v14, v0
	v_mov_b32_e32 v15, v0
	v_mov_b32_e32 v16, v0
	v_mov_b32_e32 v17, v0
	v_mov_b32_e32 v18, v0
	v_mov_b32_e32 v19, v0
	v_mov_b32_e32 v20, v0
	v_mov_b32_e32 v21, v0
	v_mov_b32_e32 v22, v0
	v_mov_b32_e32 v23, v0
	v_mov_b32_e32 v24, v0
	v_mov_b32_e32 v25, v0
	v_mov_b32_e32 v26, v0
	v_mov_b32_e32 v27, v0
	v_mov_b32_e32 v28, v0
	v_mov_b32_e32 v29, v0
	v_mov_b32_e32 v30, v0
	v_mov_b32_e32 v31, v0
	v_mov_b32_e32 v64, v0
	v_mov_b32_e32 v65, v0
	v_mov_b32_e32 v66, v0
	v_mov_b32_e32 v67, v0
	v_mov_b32_e32 v68, v0
	v_mov_b32_e32 v69, v0
	v_mov_b32_e32 v70, v0
	v_mov_b32_e32 v71, v0
	v_mov_b32_e32 v72, v0
	v_mov_b32_e32 v73, v0
	v_mov_b32_e32 v74, v0
	v_mov_b32_e32 v75, v0
	v_mov_b32_e32 v76, v0
	v_mov_b32_e32 v77, v0
	v_mov_b32_e32 v78, v0
	v_mov_b32_e32 v79, v0
	v_mov_b32_e32 v80, v0
	v_mov_b32_e32 v81, v0
	v_mov_b32_e32 v82, v0
	v_mov_b32_e32 v83, v0
	v_mov_b32_e32 v84, v0
	v_mov_b32_e32 v85, v0
	v_mov_b32_e32 v86, v0
	v_mov_b32_e32 v87, v0
	v_mov_b32_e32 v88, v0
	v_mov_b32_e32 v89, v0
	v_mov_b32_e32 v90, v0
	v_mov_b32_e32 v91, v0
	v_mov_b32_e32 v92, v0
	v_mov_b32_e32 v93, v0
	v_mov_b32_e32 v94, v0
	v_mov_b32_e32 v95, v0
	v_mov_b32_e32 v32, v0
	v_mov_b32_e32 v33, v0
	v_mov_b32_e32 v34, v0
	v_mov_b32_e32 v35, v0
	v_mov_b32_e32 v36, v0
	v_mov_b32_e32 v37, v0
	v_mov_b32_e32 v38, v0
	v_mov_b32_e32 v39, v0
	v_mov_b32_e32 v40, v0
	v_mov_b32_e32 v41, v0
	v_mov_b32_e32 v42, v0
	v_mov_b32_e32 v43, v0
	v_mov_b32_e32 v44, v0
	v_mov_b32_e32 v45, v0
	v_mov_b32_e32 v46, v0
	v_mov_b32_e32 v47, v0
	v_mov_b32_e32 v48, v0
	v_mov_b32_e32 v49, v0
	v_mov_b32_e32 v50, v0
	v_mov_b32_e32 v51, v0
	v_mov_b32_e32 v52, v0
	v_mov_b32_e32 v53, v0
	v_mov_b32_e32 v54, v0
	v_mov_b32_e32 v55, v0
	v_mov_b32_e32 v56, v0
	v_mov_b32_e32 v57, v0
	v_mov_b32_e32 v58, v0
	v_mov_b32_e32 v59, v0
	v_mov_b32_e32 v60, v0
	v_mov_b32_e32 v61, v0
	v_mov_b32_e32 v62, v0
	v_mov_b32_e32 v63, v0
	v_mov_b32_e32 v96, v0
	v_mov_b32_e32 v97, v0
	v_mov_b32_e32 v98, v0
	v_mov_b32_e32 v99, v0
	v_mov_b32_e32 v100, v0
	v_mov_b32_e32 v101, v0
	v_mov_b32_e32 v102, v0
	v_mov_b32_e32 v103, v0
	v_mov_b32_e32 v104, v0
	v_mov_b32_e32 v105, v0
	v_mov_b32_e32 v106, v0
	v_mov_b32_e32 v107, v0
	v_mov_b32_e32 v108, v0
	v_mov_b32_e32 v109, v0
	v_mov_b32_e32 v110, v0
	v_mov_b32_e32 v111, v0
	v_mov_b32_e32 v112, v0
	v_mov_b32_e32 v113, v0
	v_mov_b32_e32 v114, v0
	v_mov_b32_e32 v115, v0
	v_mov_b32_e32 v116, v0
	v_mov_b32_e32 v117, v0
	v_mov_b32_e32 v118, v0
	v_mov_b32_e32 v119, v0
	v_mov_b32_e32 v120, v0
	v_mov_b32_e32 v121, v0
	v_mov_b32_e32 v122, v0
	v_mov_b32_e32 v123, v0
	v_mov_b32_e32 v124, v0
	v_mov_b32_e32 v125, v0
	v_mov_b32_e32 v126, v0
	v_mov_b32_e32 v127, v0
	.p2align	6

; DI u32 pk2(float a, float b) { f2_t v = {a, b}; bf2_t r = __builtin_convertvector(v, bf2_t); return __builtin_bit_cast(u32, r); }
; DI float bflo(u32 u) { return __uint_as_float(u << 16); }
; DI float bfhi(u32 u) { return __uint_as_float(u & 0xffff0000u); }
; DI float xor32_sum(float v) { auto rr = __builtin_amdgcn_permlane32_swap(__float_as_uint(v), __float_as_uint(v), false, false); return __uint_as_float(rr[0]) + __uint_as_float(rr[1]); }
; template <bool DIFF>
; DI void attn_phase(const AttnArgs& a, char* lds) {
;     ...
;       if (DIFF) {
;         float ss = 0.f;
; #pragma unroll
;         for (int ds = 0; ds < NDS; ++ds) {
;           const u32x4 w = __builtin_bit_cast(u32x4, qf[ds]);
; #pragma unroll
;           for (int i = 0; i < 4; ++i) { const float x0 = bflo(w[i]), x1 = bfhi(w[i]); ss += x0 * x0 + x1 * x1; }
;         }
;         ss = xor32_sum(ss);
;         const float ri = rsqrtf(ss * (1.0f / 128.0f) + EPS) * QSCALE_B;
; #pragma unroll
;         for (int ds = 0; ds < NDS; ++ds) {
;           const u32x4 w = __builtin_bit_cast(u32x4, qf[ds]);
;           const float4 ga = *(const float4*)(a.qgain + ds * 16 + (tq >> 5) * 8), gb = *(const float4*)(a.qgain + ds * 16 + (tq >> 5) * 8 + 4);
;           u32x4 o4;
;           o4[0] = pk2(bflo(w[0]) * ri * ga.x, bfhi(w[0]) * ri * ga.y); o4[1] = pk2(bflo(w[1]) * ri * ga.z, bfhi(w[1]) * ri * ga.w);
;           o4[2] = pk2(bflo(w[2]) * ri * gb.x, bfhi(w[2]) * ri * gb.y); o4[3] = pk2(bflo(w[3]) * ri * gb.z, bfhi(w[3]) * ri * gb.w);
;           qf[ds] = __builtin_bit_cast(bf16x8, o4);
;         }
.LBB0_597:
	s_andn2_b64 vcc, exec, s[66:67]
	s_waitcnt vmcnt(0) lgkmcnt(0)
	s_barrier
	s_cbranch_vccnz .LBB0_630
	v_add_f32_e32 v0, v136, v87
	v_fmamk_f32 v0, v0, 0x3c000000, v212
	v_mul_f32_e32 v87, 0x4b800000, v0
	v_cmp_gt_f32_e32 vcc, s72, v0
	v_mov_b32_e32 v89, v95
	v_mov_b32_e32 v95, v117
	v_cndmask_b32_e32 v0, v0, v87, vcc
	v_rsq_f32_e32 v0, v0
	v_mov_b32_e32 v87, v97
	v_mov_b32_e32 v97, v119
	v_mov_b32_e32 v91, v93
	v_mul_f32_e32 v116, 0x45800000, v0
	v_cndmask_b32_e32 v0, v0, v116, vcc
	v_mul_f32_e32 v0, 0x3e0293ee, v0
	v_pk_mul_f32 v[116:117], v[0:1], v[134:135] op_sel_hi:[0,1]
	v_pk_mul_f32 v[62:63], v[62:63], v[116:117]
	v_mov_b32_e32 v93, v123
	v_cvt_pk_bf16_f32 v176, v62, v63
	v_pk_mul_f32 v[62:63], v[0:1], v[132:133] op_sel_hi:[0,1]
	v_pk_mul_f32 v[62:63], v[64:65], v[62:63]
	s_add_i32 s4, s0, 1
	v_cvt_pk_bf16_f32 v177, v62, v63
	v_pk_mul_f32 v[62:63], v[0:1], v[130:131] op_sel_hi:[0,1]
	v_pk_mul_f32 v[58:59], v[58:59], v[62:63]
	v_cvt_f32_i32_e32 v221, v138
	v_cvt_pk_bf16_f32 v178, v58, v59
	v_pk_mul_f32 v[58:59], v[0:1], v[128:129] op_sel_hi:[0,1]
	v_pk_mul_f32 v[58:59], v[60:61], v[58:59]
	v_cndmask_b32_e64 v222, 0, 1, s[8:9]
	v_cvt_pk_bf16_f32 v179, v58, v59
	v_pk_mul_f32 v[58:59], v[0:1], v[126:127] op_sel_hi:[0,1]
	v_pk_mul_f32 v[54:55], v[54:55], v[58:59]
	v_cndmask_b32_e64 v225, v215, 0, s[8:9]
	v_cvt_pk_bf16_f32 v180, v54, v55
	v_pk_mul_f32 v[54:55], v[0:1], v[124:125] op_sel_hi:[0,1]
	v_pk_mul_f32 v[54:55], v[56:57], v[54:55]
	v_mov_b32_e32 v226, 0
	v_cvt_pk_bf16_f32 v181, v54, v55
	v_pk_mul_f32 v[54:55], v[0:1], v[120:121] op_sel_hi:[0,1]
	v_pk_mul_f32 v[50:51], v[54:55], v[50:51]
	s_nop 0
	v_cvt_pk_bf16_f32 v182, v50, v51
	v_pk_mul_f32 v[50:51], v[0:1], v[66:67] op_sel_hi:[0,1]
	v_pk_mul_f32 v[50:51], v[50:51], v[52:53]
	s_nop 0
	v_cvt_pk_bf16_f32 v183, v50, v51
	v_pk_mul_f32 v[50:51], v[0:1], v[114:115] op_sel_hi:[0,1]
	v_pk_mul_f32 v[46:47], v[50:51], v[46:47]
	s_nop 0
	v_cvt_pk_bf16_f32 v184, v46, v47
	v_pk_mul_f32 v[46:47], v[0:1], v[68:69] op_sel_hi:[0,1]
	v_pk_mul_f32 v[46:47], v[46:47], v[48:49]
	s_nop 0
	v_cvt_pk_bf16_f32 v185, v46, v47
	v_pk_mul_f32 v[46:47], v[0:1], v[112:113] op_sel_hi:[0,1]
	v_pk_mul_f32 v[42:43], v[46:47], v[42:43]
	s_nop 0
	v_cvt_pk_bf16_f32 v186, v42, v43
	v_pk_mul_f32 v[42:43], v[0:1], v[70:71] op_sel_hi:[0,1]
	v_pk_mul_f32 v[42:43], v[42:43], v[44:45]
	s_nop 0
	v_cvt_pk_bf16_f32 v187, v42, v43
	v_pk_mul_f32 v[42:43], v[0:1], v[110:111] op_sel_hi:[0,1]
	v_pk_mul_f32 v[38:39], v[42:43], v[38:39]
	s_nop 0
	v_cvt_pk_bf16_f32 v188, v38, v39
	v_pk_mul_f32 v[38:39], v[0:1], v[72:73] op_sel_hi:[0,1]
	v_pk_mul_f32 v[38:39], v[38:39], v[40:41]
	s_nop 0
	v_cvt_pk_bf16_f32 v189, v38, v39
	v_pk_mul_f32 v[38:39], v[0:1], v[108:109] op_sel_hi:[0,1]
	v_pk_mul_f32 v[34:35], v[38:39], v[34:35]
	s_nop 0
	v_cvt_pk_bf16_f32 v190, v34, v35
	v_pk_mul_f32 v[34:35], v[0:1], v[74:75] op_sel_hi:[0,1]
	v_pk_mul_f32 v[34:35], v[34:35], v[36:37]
	s_nop 0
	v_cvt_pk_bf16_f32 v191, v34, v35
	v_pk_mul_f32 v[34:35], v[0:1], v[106:107] op_sel_hi:[0,1]
	v_pk_mul_f32 v[30:31], v[34:35], v[30:31]
	s_nop 0
	v_cvt_pk_bf16_f32 v192, v30, v31
	v_pk_mul_f32 v[30:31], v[0:1], v[76:77] op_sel_hi:[0,1]
	v_pk_mul_f32 v[30:31], v[30:31], v[32:33]
	s_nop 0
	v_cvt_pk_bf16_f32 v193, v30, v31
	v_pk_mul_f32 v[30:31], v[0:1], v[104:105] op_sel_hi:[0,1]
	v_pk_mul_f32 v[26:27], v[30:31], v[26:27]
	s_nop 0
	v_cvt_pk_bf16_f32 v194, v26, v27
	v_pk_mul_f32 v[26:27], v[0:1], v[78:79] op_sel_hi:[0,1]
	v_pk_mul_f32 v[26:27], v[26:27], v[28:29]
	s_nop 0
	v_cvt_pk_bf16_f32 v195, v26, v27
	v_pk_mul_f32 v[26:27], v[0:1], v[102:103] op_sel_hi:[0,1]
	v_pk_mul_f32 v[22:23], v[26:27], v[22:23]
	s_nop 0
	v_cvt_pk_bf16_f32 v196, v22, v23
	v_pk_mul_f32 v[22:23], v[0:1], v[80:81] op_sel_hi:[0,1]
	v_pk_mul_f32 v[22:23], v[22:23], v[24:25]
	s_nop 0
	v_cvt_pk_bf16_f32 v197, v22, v23
	v_pk_mul_f32 v[22:23], v[0:1], v[100:101] op_sel_hi:[0,1]
	v_pk_mul_f32 v[18:19], v[22:23], v[18:19]
	s_nop 0
	v_cvt_pk_bf16_f32 v198, v18, v19
	v_pk_mul_f32 v[18:19], v[0:1], v[82:83] op_sel_hi:[0,1]
	v_pk_mul_f32 v[18:19], v[18:19], v[20:21]
	s_nop 0
; DI u32 pk2(float a, float b) { f2_t v = {a, b}; bf2_t r = __builtin_convertvector(v, bf2_t); return __builtin_bit_cast(u32, r); }
; DI float bflo(u32 u) { return __uint_as_float(u << 16); }
; DI float bfhi(u32 u) { return __uint_as_float(u & 0xffff0000u); }
; template <bool DIFF>
; DI void attn_phase(const AttnArgs& a, char* lds) {
;     ...
;         for (int ds = 0; ds < NDS; ++ds) {
;           const u32x4 w = __builtin_bit_cast(u32x4, qf[ds]);
;           const float4 ga = *(const float4*)(a.qgain + ds * 16 + (tq >> 5) * 8), gb = *(const float4*)(a.qgain + ds * 16 + (tq >> 5) * 8 + 4);
;           u32x4 o4;
;           o4[0] = pk2(bflo(w[0]) * ri * ga.x, bfhi(w[0]) * ri * ga.y); o4[1] = pk2(bflo(w[1]) * ri * ga.z, bfhi(w[1]) * ri * ga.w);
;           o4[2] = pk2(bflo(w[2]) * ri * gb.x, bfhi(w[2]) * ri * gb.y); o4[3] = pk2(bflo(w[3]) * ri * gb.z, bfhi(w[3]) * ri * gb.w);
;           qf[ds] = __builtin_bit_cast(bf16x8, o4);
;         }
;       }
;     }
;     const int g32 = __builtin_amdgcn_readfirstlane((qb * QROWS + rg * 32) >> 5);
;     const int wqcmin = c32[g32], wqcmax = c32[512 + g32];
;     int t_end = c32[C_TEND + qb * (QROWS / 32)];
; #pragma unroll
;     for (int i = 1; i < QROWS / 32; ++i) t_end = max(t_end, c32[C_TEND + qb * (QROWS / 32) + i]);
;     t_end = __builtin_amdgcn_readfirstlane(t_end);
;     int t_beg = 0;
;     int wpmin = 0, wpmax = 0;
;     float lim2 = 0.f;
;     if (DIFF) {
;       t_beg = c32[C_TBEG + h * 512 + qb * 4];
; #pragma unroll
;       for (int i = 1; i < 4; ++i) t_beg = min(t_beg, c32[C_TBEG + h * 512 + qb * 4 + i]);
;       t_beg = __builtin_amdgcn_readfirstlane(t_beg);
;       wpmin = c32[C_PMIN + g32]; wpmax = c32[C_PMAX + g32];
;       lim2 = a.lamtab[2];
;     }
;     const float slope2 = DIFF ? exp2f(-(float)(h + 1)) * LOG2E : 0.f;
;     ...
;     f32x16 o[NM];
; #pragma unroll
;     for (int m = 0; m < NM; ++m)
; #pragma unroll
;       for (int r = 0; r < 16; ++r) o[m][r] = 0.f;
;     const float sbound = a.lamtab_all[DIFF ? 4 : 3];
;     const int usefix_i = __builtin_amdgcn_readfirstlane(sbound < 40.0f ? 1 : 0);
;     const bool usefix = usefix_i != 0;
;     float m_ref = usefix ? 0.f : -1e30f, l_sum = 0.f;
;     f32x16 negm;
; #pragma unroll
;     for (int r = 0; r < 16; ++r) negm[r] = 0.f;
	v_cvt_pk_bf16_f32 v199, v18, v19
	v_pk_mul_f32 v[18:19], v[0:1], v[98:99] op_sel_hi:[0,1]
	v_pk_mul_f32 v[14:15], v[18:19], v[14:15]
	s_nop 0
	v_cvt_pk_bf16_f32 v200, v14, v15
	v_pk_mul_f32 v[14:15], v[0:1], v[84:85] op_sel_hi:[0,1]
	v_pk_mul_f32 v[14:15], v[14:15], v[16:17]
	s_nop 0
	v_cvt_pk_bf16_f32 v201, v14, v15
	v_pk_mul_f32 v[14:15], v[0:1], v[96:97] op_sel_hi:[0,1]
	v_pk_mul_f32 v[10:11], v[14:15], v[10:11]
	v_mov_b32_e32 v14, v1
	v_cvt_pk_bf16_f32 v202, v10, v11
	v_pk_mul_f32 v[10:11], v[0:1], v[86:87] op_sel_hi:[0,1]
	v_pk_mul_f32 v[10:11], v[10:11], v[12:13]
	v_mov_b32_e32 v15, v1
	v_cvt_pk_bf16_f32 v203, v10, v11
	v_pk_mul_f32 v[10:11], v[0:1], v[94:95] op_sel_hi:[0,1]
	v_pk_mul_f32 v[6:7], v[10:11], v[6:7]
	v_mov_b32_e32 v10, v1
	v_cvt_pk_bf16_f32 v204, v6, v7
	v_pk_mul_f32 v[6:7], v[0:1], v[88:89] op_sel_hi:[0,1]
	v_pk_mul_f32 v[6:7], v[6:7], v[8:9]
	v_mov_b32_e32 v8, v1
	v_cvt_pk_bf16_f32 v205, v6, v7
	v_pk_mul_f32 v[6:7], v[0:1], v[92:93] op_sel_hi:[0,1]
	v_pk_mul_f32 v[2:3], v[6:7], v[2:3]
	v_cvt_f32_i32_e32 v6, s4
	v_cvt_pk_bf16_f32 v206, v2, v3
	v_pk_mul_f32 v[2:3], v[0:1], v[90:91] op_sel_hi:[0,1]
	v_pk_mul_f32 v[2:3], v[2:3], v[4:5]
	v_cmp_lt_f32_e32 vcc, s73, v6
	s_and_b64 s[4:5], vcc, exec
	s_cselect_b32 s4, 0xffffffc0, 0
	v_cndmask_b32_e32 v0, 0, v214, vcc
	v_sub_f32_e32 v0, v0, v6
	v_exp_f32_e32 v0, v0
	s_lshl_b32 s0, s0, 22
	v_cvt_pk_bf16_f32 v207, v2, v3
	v_mov_b32_e32 v2, v1
	v_ldexp_f32 v0, v0, s4
	v_mul_f32_e32 v223, 0x3fb8aa3b, v0
	v_cvt_i32_f32_e32 v0, v221
	s_lshl_b32 s4, s1, 4
	s_add_i32 s80, s4, 0x20ff0
	s_lshl_b32 s4, s1, 6
	s_add_i32 s81, s4, 64
	s_lshl_b32 s4, s1, 14
	v_ashrrev_i32_e32 v224, 6, v0
	s_add_i32 s0, s0, s4
	v_mov_b32_e32 v0, v1
	v_mov_b32_e32 v3, v1
	v_mov_b32_e32 v4, v1
	v_mov_b32_e32 v5, v1
	v_mov_b32_e32 v6, v1
	v_mov_b32_e32 v7, v1
	v_mov_b32_e32 v9, v1
	v_mov_b32_e32 v11, v1
	v_mov_b32_e32 v12, v1
	v_mov_b32_e32 v13, v1
	v_mov_b64_e32 v[30:31], v[14:15]
	v_mov_b64_e32 v[46:47], v[14:15]
	v_mov_b64_e32 v[62:63], v[14:15]
	v_mov_b64_e32 v[78:79], v[14:15]
	v_mov_b64_e32 v[94:95], v[14:15]
	v_mov_b64_e32 v[110:111], v[14:15]
	v_mov_b64_e32 v[126:127], v[14:15]
	v_mov_b64_e32 v[142:143], v[14:15]
	s_add_i32 s79, s75, 0x800
	s_add_i32 s82, s0, 0x4000
	v_mov_b64_e32 v[28:29], v[12:13]
	v_mov_b64_e32 v[26:27], v[10:11]
	v_mov_b64_e32 v[24:25], v[8:9]
	v_mov_b64_e32 v[22:23], v[6:7]
	v_mov_b64_e32 v[20:21], v[4:5]
	v_mov_b64_e32 v[18:19], v[2:3]
	v_mov_b64_e32 v[16:17], v[0:1]
	v_mov_b64_e32 v[44:45], v[12:13]
	v_mov_b64_e32 v[42:43], v[10:11]
	v_mov_b64_e32 v[40:41], v[8:9]
	v_mov_b64_e32 v[38:39], v[6:7]
	v_mov_b64_e32 v[36:37], v[4:5]
	v_mov_b64_e32 v[34:35], v[2:3]
	v_mov_b64_e32 v[32:33], v[0:1]
	v_mov_b64_e32 v[60:61], v[12:13]
	v_mov_b64_e32 v[58:59], v[10:11]
	v_mov_b64_e32 v[56:57], v[8:9]
	v_mov_b64_e32 v[54:55], v[6:7]
	v_mov_b64_e32 v[52:53], v[4:5]
	v_mov_b64_e32 v[50:51], v[2:3]
	v_mov_b64_e32 v[48:49], v[0:1]
	v_mov_b64_e32 v[76:77], v[12:13]
	v_mov_b64_e32 v[74:75], v[10:11]
	v_mov_b64_e32 v[72:73], v[8:9]
	v_mov_b64_e32 v[70:71], v[6:7]
	v_mov_b64_e32 v[68:69], v[4:5]
	v_mov_b64_e32 v[66:67], v[2:3]
	v_mov_b64_e32 v[64:65], v[0:1]
	v_mov_b64_e32 v[92:93], v[12:13]
	v_mov_b64_e32 v[90:91], v[10:11]
	v_mov_b64_e32 v[88:89], v[8:9]
	v_mov_b64_e32 v[86:87], v[6:7]
	v_mov_b64_e32 v[84:85], v[4:5]
	v_mov_b64_e32 v[82:83], v[2:3]
	v_mov_b64_e32 v[80:81], v[0:1]
	v_mov_b64_e32 v[108:109], v[12:13]
	v_mov_b64_e32 v[106:107], v[10:11]
	v_mov_b64_e32 v[104:105], v[8:9]
	v_mov_b64_e32 v[102:103], v[6:7]
	v_mov_b64_e32 v[100:101], v[4:5]
	v_mov_b64_e32 v[98:99], v[2:3]
	v_mov_b64_e32 v[96:97], v[0:1]
	v_mov_b64_e32 v[124:125], v[12:13]
	v_mov_b64_e32 v[122:123], v[10:11]
	v_mov_b64_e32 v[120:121], v[8:9]
	v_mov_b64_e32 v[118:119], v[6:7]
	v_mov_b64_e32 v[116:117], v[4:5]
	v_mov_b64_e32 v[114:115], v[2:3]
	v_mov_b64_e32 v[112:113], v[0:1]
	v_mov_b64_e32 v[140:141], v[12:13]
	v_mov_b64_e32 v[138:139], v[10:11]
	v_mov_b64_e32 v[136:137], v[8:9]
	v_mov_b64_e32 v[134:135], v[6:7]
	v_mov_b64_e32 v[132:133], v[4:5]
	v_mov_b64_e32 v[130:131], v[2:3]
	v_mov_b64_e32 v[128:129], v[0:1]
	.p2align	6

; #define PG8_STAGE(bufoff, gbase, voff) do { _Pragma("unroll") for (int _i = 0; _i < 2; ++_i) \
;     __builtin_amdgcn_global_load_lds((const unsigned*)((const char*)(gbase) + (voff)[_i]), (PG8_LAS unsigned*)(lds + (bufoff) + ldsw + _i * 8192), 16, 0, 0); } while (0)
; #define PG8_WAIT_V(n) asm volatile("s_waitcnt vmcnt(" #n ")" ::: "memory")
; #define PG8_BAR __builtin_amdgcn_s_barrier()
; template <class Epi>
; DI void gemm_phase(PG8_LAS unsigned char* lds, const Gemm g, const StaticOrder& S, const Epi& E) {
;     ...
;   f32x4 acc[2][2][4][2];
; #pragma unroll
;   for (int a = 0; a < 2; ++a)
; #pragma unroll
;     for (int b = 0; b < 2; ++b)
; #pragma unroll
;       for (int m = 0; m < 4; ++m)
; #pragma unroll
;         for (int n = 0; n < 2; ++n) acc[a][b][m][n] = (f32x4){0.f, 0.f, 0.f, 0.f};
;   bf16x8 At[4][2], B0[2][2], B1[2][2];
;   const char* cA = (const char*)g.A + (size_t)cur.pm * tstepA; const char* cB = (const char*)g.Bt + (size_t)cur.pn * tstepB;
;   PG8_WAIT_V(0);
;   PG8_STAGE(PG8_SB(0, 0), cB, voffB); PG8_STAGE(PG8_SA(0, 0), cA, voffA); PG8_STAGE(PG8_SB(0, 1), cB + hstepB, voffB); PG8_STAGE(PG8_SA(0, 1), cA + hstepA, voffA);
;   if (wr == 1) PG8_BAR;
;   PG8_WAIT_V(4); PG8_BAR;
;   PG8_STAGE(PG8_SB(1, 0), cB + kstep, voffB); PG8_STAGE(PG8_SA(1, 0), cA + kstep, voffA); PG8_STAGE(PG8_SB(1, 1), cB + hstepB + kstep, voffB);
;   PG8_WAIT_V(6); PG8_BAR;
; #pragma unroll 1
;   for (;;) {
;     const bool has_next = S.next(ui + 1, nxt);
;     const char* nA = has_next ? (const char*)g.A + (size_t)nxt.pm * tstepA : cA; const char* nB = has_next ? (const char*)g.Bt + (size_t)nxt.pn * tstepB : cB;
; #pragma unroll 1
;     for (int t = 0; t < nt; t += 2) {
.LBB0_659:
	s_ashr_i32 s9, s8, 31
	v_cmp_lt_i64_e32 vcc, s[10:11], v[142:143]
	s_lshl_b64 s[10:11], s[8:9], 20
	s_add_u32 s10, s24, s10
	s_addc_u32 s11, s25, s11
	s_and_b64 s[12:13], vcc, exec
	s_cselect_b32 s9, s11, s17
	s_cselect_b32 s47, s10, s16
	s_ashr_i32 s7, s6, 31
	s_lshl_b64 s[12:13], s[6:7], 20
	s_add_u32 s12, s90, s12
	s_addc_u32 s13, s91, s13
	s_and_b64 s[20:21], vcc, exec
	s_cselect_b32 s7, s13, s19
	s_cselect_b32 s48, s12, s18
	s_add_u32 s16, s16, 0x80080
	s_addc_u32 s17, s17, 0
	s_add_u32 s49, s18, 0x100
	v_mov_b32_e32 v0, 0
	s_addc_u32 s52, s19, 0
	s_mov_b32 s53, -2
	v_mov_b32_e32 v1, v0
	v_mov_b32_e32 v2, v0
	v_mov_b32_e32 v3, v0
	v_mov_b32_e32 v4, v0
	v_mov_b32_e32 v5, v0
	v_mov_b32_e32 v6, v0
	v_mov_b32_e32 v7, v0
	v_mov_b32_e32 v16, v0
	v_mov_b32_e32 v17, v0
	v_mov_b32_e32 v18, v0
	v_mov_b32_e32 v19, v0
	v_mov_b32_e32 v20, v0
	v_mov_b32_e32 v21, v0
	v_mov_b32_e32 v22, v0
	v_mov_b32_e32 v23, v0
	v_mov_b32_e32 v32, v0
	v_mov_b32_e32 v33, v0
	v_mov_b32_e32 v34, v0
	v_mov_b32_e32 v35, v0
	v_mov_b32_e32 v36, v0
	v_mov_b32_e32 v37, v0
	v_mov_b32_e32 v38, v0
	v_mov_b32_e32 v39, v0
	v_mov_b32_e32 v48, v0
	v_mov_b32_e32 v49, v0
	v_mov_b32_e32 v50, v0
	v_mov_b32_e32 v51, v0
	v_mov_b32_e32 v52, v0
	v_mov_b32_e32 v53, v0
	v_mov_b32_e32 v54, v0
	v_mov_b32_e32 v55, v0
	v_mov_b32_e32 v8, v0
	v_mov_b32_e32 v9, v0
	v_mov_b32_e32 v10, v0
	v_mov_b32_e32 v11, v0
	v_mov_b32_e32 v12, v0
	v_mov_b32_e32 v13, v0
	v_mov_b32_e32 v14, v0
	s_waitcnt vmcnt(0)
	v_mov_b32_e32 v15, v0
	v_mov_b32_e32 v24, v0
	v_mov_b32_e32 v25, v0
	v_mov_b32_e32 v26, v0
	v_mov_b32_e32 v27, v0
	v_mov_b32_e32 v28, v0
	v_mov_b32_e32 v29, v0
	v_mov_b32_e32 v30, v0
	v_mov_b32_e32 v31, v0
	v_mov_b32_e32 v40, v0
	v_mov_b32_e32 v41, v0
	v_mov_b32_e32 v42, v0
	v_mov_b32_e32 v43, v0
	v_mov_b32_e32 v44, v0
	v_mov_b32_e32 v45, v0
	v_mov_b32_e32 v46, v0
	v_mov_b32_e32 v47, v0
	v_mov_b32_e32 v56, v0
	v_mov_b32_e32 v57, v0
	v_mov_b32_e32 v58, v0
	v_mov_b32_e32 v59, v0
	v_mov_b32_e32 v60, v0
	v_mov_b32_e32 v61, v0
	v_mov_b32_e32 v62, v0
	v_mov_b32_e32 v63, v0
	v_mov_b32_e32 v64, v0
	v_mov_b32_e32 v65, v0
	v_mov_b32_e32 v66, v0
	v_mov_b32_e32 v67, v0
	v_mov_b32_e32 v68, v0
	v_mov_b32_e32 v69, v0
	v_mov_b32_e32 v70, v0
	v_mov_b32_e32 v71, v0
	v_mov_b32_e32 v80, v0
	v_mov_b32_e32 v81, v0
	v_mov_b32_e32 v82, v0
	v_mov_b32_e32 v83, v0
	v_mov_b32_e32 v84, v0
	v_mov_b32_e32 v85, v0
	v_mov_b32_e32 v86, v0
	v_mov_b32_e32 v87, v0
	v_mov_b32_e32 v96, v0
	v_mov_b32_e32 v97, v0
	v_mov_b32_e32 v98, v0
	v_mov_b32_e32 v99, v0
	v_mov_b32_e32 v100, v0
	v_mov_b32_e32 v101, v0
	v_mov_b32_e32 v102, v0
	v_mov_b32_e32 v103, v0
	v_mov_b32_e32 v112, v0
	v_mov_b32_e32 v113, v0
	v_mov_b32_e32 v114, v0
	v_mov_b32_e32 v115, v0
	v_mov_b32_e32 v116, v0
	v_mov_b32_e32 v117, v0
	v_mov_b32_e32 v118, v0
	v_mov_b32_e32 v119, v0
	v_mov_b32_e32 v72, v0
	v_mov_b32_e32 v73, v0
	v_mov_b32_e32 v74, v0
	v_mov_b32_e32 v75, v0
	v_mov_b32_e32 v76, v0
	v_mov_b32_e32 v77, v0
	v_mov_b32_e32 v78, v0
	v_mov_b32_e32 v79, v0
	v_mov_b32_e32 v88, v0
	v_mov_b32_e32 v89, v0
	v_mov_b32_e32 v90, v0
	v_mov_b32_e32 v91, v0
	v_mov_b32_e32 v92, v0
	v_mov_b32_e32 v93, v0
	v_mov_b32_e32 v94, v0
	v_mov_b32_e32 v95, v0
	v_mov_b32_e32 v104, v0
	v_mov_b32_e32 v105, v0
	v_mov_b32_e32 v106, v0
	v_mov_b32_e32 v107, v0
	v_mov_b32_e32 v108, v0
	v_mov_b32_e32 v109, v0
	v_mov_b32_e32 v110, v0
	v_mov_b32_e32 v111, v0
	v_mov_b32_e32 v120, v0
	v_mov_b32_e32 v121, v0
	v_mov_b32_e32 v122, v0
	v_mov_b32_e32 v123, v0
	v_mov_b32_e32 v124, v0
	v_mov_b32_e32 v125, v0
	v_mov_b32_e32 v126, v0
	v_mov_b32_e32 v127, v0
	.p2align	6
